# FF2 stream-K segment lengths 48 (64 workgroups) / 32 (160): short-segment workgroups reach their epilogues while long-segment ones are still in the K-loop
# speedup vs baseline: 1.0005x; 1.0005x over previous
.LBB0_411:
	s_or_b64 exec, exec, s[0:1]
	s_cmpk_lt_i32 s2, 0x330
	s_mul_hi_i32 s0, s2, 0xa0a0a0a1
	s_cselect_b64 s[26:27], -1, 0
	s_add_i32 s0, s0, s2
	s_lshr_b32 s1, s0, 31
	s_lshr_b32 s0, s0, 9
	s_add_i32 s0, s0, s1
	s_mulk_i32 s0, 0x330
	s_sub_i32 s0, s2, s0
	s_sext_i32_i16 s1, s0
	s_bfe_u32 s1, s1, 0x3001c
	s_add_i32 s1, s0, s1
	s_sext_i32_i16 s3, s1
	s_and_b32 s1, s1, 0xfff8
	s_ashr_i32 s6, s3, 3
	s_sub_i32 s8, s0, s1
	s_sub_i32 s80, s94, 48
	s_sub_i32 s0, s2, 48
	s_cmp_gt_u32 s2, 47
	s_cselect_b32 s81, s0, 0x10000000
	s_cmpk_lt_i32 s81, 0x198
	s_cselect_b64 s[0:1], -1, 0
	v_writelane_b32 v245, s0, 3
	s_waitcnt lgkmcnt(0)
	v_mov_b32_e32 v0, 0xe0
	v_sub_co_u32_e32 v0, vcc, s2, v0
	v_writelane_b32 v245, s1, 4
	s_mul_hi_i32 s0, s81, 0xa0a0a0a1
	s_add_i32 s0, s0, s81
	s_lshr_b32 s1, s0, 31
	s_lshr_b32 s0, s0, 8
	s_add_i32 s0, s0, s1
	s_mulk_i32 s0, 0x198
	s_sub_i32 s0, s81, s0
	s_sext_i32_i16 s1, s0
	s_bfe_u32 s1, s1, 0x3001c
	s_add_i32 s1, s0, s1
	s_sext_i32_i16 s3, s1
	s_and_b32 s1, s1, 0xfff8
	s_ashr_i32 s5, s3, 3
	s_sub_i32 s7, s0, s1
	s_cmpk_lt_i32 s2, 0x110
	s_cselect_b64 s[0:1], -1, 0
	v_writelane_b32 v245, s0, 5
	s_bfe_u32 s87, s2, 0x50002
	s_lshr_b32 s3, s2, 2
	v_writelane_b32 v245, s1, 6
	s_and_b32 s0, s2, 3
	s_lshl_b32 s89, s87, 6
	s_lshl_b32 s1, s0, 2
	s_lshl_b32 s0, s0, 8
	s_cmp_lg_u32 s87, 0
	v_writelane_b32 v245, s1, 7
	s_cselect_b64 s[36:37], -1, 0
	s_cmp_eq_u32 s87, 31
	v_writelane_b32 v245, s0, 8
	s_cselect_b64 s[38:39], -1, 0
	s_lshl_b32 s0, s2, 8
	s_and_b32 s0, s0, 0x300
	s_cmp_eq_u32 s87, 0
	v_writelane_b32 v245, s0, 9
	s_cselect_b64 s[0:1], -1, 0
	v_writelane_b32 v245, s0, 10
	s_cmp_gt_u32 s87, 1
	s_movk_i32 s93, 0x67
	v_writelane_b32 v245, s1, 11
	s_cselect_b64 s[0:1], -1, 0
	v_writelane_b32 v245, s0, 12
	s_cmp_gt_u32 s87, 2
	v_mov_b32_e32 v185, 0
	v_writelane_b32 v245, s1, 13
	s_cselect_b64 s[0:1], -1, 0
	v_writelane_b32 v245, s0, 14
	s_cmp_gt_u32 s87, 3
	v_mov_b32_e32 v216, 0x358637bd
	v_writelane_b32 v245, s1, 15
	s_cselect_b64 s[0:1], -1, 0
	v_writelane_b32 v245, s0, 16
	s_cmp_gt_u32 s87, 4
	v_mov_b32_e32 v217, 0x1000
	v_writelane_b32 v245, s1, 17
	s_cselect_b64 s[0:1], -1, 0
	v_writelane_b32 v245, s0, 18
	s_cmp_gt_u32 s87, 5
	v_mov_b32_e32 v218, 0x2000
	v_writelane_b32 v245, s1, 19
	s_cselect_b64 s[0:1], -1, 0
	v_writelane_b32 v245, s0, 20
	s_cmp_gt_u32 s87, 6
	v_mov_b32_e32 v219, 0x11083000
	v_writelane_b32 v245, s1, 21
	s_cselect_b64 s[0:1], -1, 0
	v_writelane_b32 v245, s0, 22
	s_cmp_gt_u32 s87, 7
	v_mov_b32_e32 v220, 1
	v_writelane_b32 v245, s1, 23
	s_cselect_b64 s[0:1], -1, 0
	v_writelane_b32 v245, s0, 24
	s_cmp_gt_u32 s87, 8
	v_mov_b32_e32 v222, 0x3000
	v_writelane_b32 v245, s1, 25
	s_cselect_b64 s[0:1], -1, 0
	s_cmp_gt_u32 s87, 9
	s_cselect_b64 s[40:41], -1, 0
	s_cmp_gt_u32 s87, 10
	s_cselect_b64 s[42:43], -1, 0
	s_cmp_gt_u32 s87, 11
	s_cselect_b64 s[44:45], -1, 0
	s_cmp_gt_u32 s87, 12
	s_cselect_b64 s[46:47], -1, 0
	s_cmp_gt_u32 s87, 13
	v_writelane_b32 v245, s0, 26
	s_cselect_b64 s[48:49], -1, 0
	s_cmp_gt_u32 s87, 14
	v_writelane_b32 v245, s1, 27
	s_cselect_b64 s[0:1], -1, 0
	v_writelane_b32 v245, s0, 28
	s_cmp_gt_u32 s87, 15
	v_mov_b32_e32 v223, 0x2200
	v_writelane_b32 v245, s1, 29
	s_cselect_b64 s[0:1], -1, 0
	v_writelane_b32 v245, s0, 30
	s_cmp_gt_u32 s87, 16
	s_movk_i32 s90, 0x4000
	v_writelane_b32 v245, s1, 31
	s_cselect_b64 s[0:1], -1, 0
	v_writelane_b32 v245, s0, 32
	s_cmp_gt_u32 s87, 17
	s_movk_i32 s68, 0x4800
	v_writelane_b32 v245, s1, 33
	s_cselect_b64 s[0:1], -1, 0
	v_writelane_b32 v245, s0, 34
	s_cmp_gt_u32 s87, 18
	s_mov_b32 s69, 0xffff0000
	v_writelane_b32 v245, s1, 35
	s_cselect_b64 s[0:1], -1, 0
	v_writelane_b32 v245, s0, 36
	s_cmp_gt_u32 s87, 19
	s_movk_i32 s50, 0x3000
	v_writelane_b32 v245, s1, 37
	s_cselect_b64 s[0:1], -1, 0
	v_writelane_b32 v245, s0, 38
	s_cmp_gt_u32 s87, 20
	s_mov_b32 s52, 0
	v_writelane_b32 v245, s1, 39
	s_cselect_b64 s[0:1], -1, 0
	v_writelane_b32 v245, s0, 40
	s_cmp_gt_u32 s87, 21
	s_mov_b32 s97, 0
	v_writelane_b32 v245, s1, 41
	s_cselect_b64 s[0:1], -1, 0
	v_writelane_b32 v245, s0, 42
	s_cmp_gt_u32 s87, 22
	s_nop 0
	v_writelane_b32 v245, s1, 43
	s_cselect_b64 s[0:1], -1, 0
	v_writelane_b32 v245, s0, 44
	s_cmp_gt_u32 s87, 23
	s_barrier
	v_writelane_b32 v245, s1, 45
	s_cselect_b64 s[0:1], -1, 0
	v_writelane_b32 v245, s0, 46
	s_cmp_gt_u32 s87, 24
	s_nop 0
	v_writelane_b32 v245, s1, 47
	s_cselect_b64 s[0:1], -1, 0
	v_writelane_b32 v245, s0, 48
	s_cmp_gt_u32 s87, 25
	s_nop 0
	v_writelane_b32 v245, s1, 49
	s_cselect_b64 s[0:1], -1, 0
	v_writelane_b32 v245, s0, 50
	s_cmp_gt_u32 s87, 26
	s_nop 0
	v_writelane_b32 v245, s1, 51
	s_cselect_b64 s[0:1], -1, 0
	v_writelane_b32 v245, s0, 52
	s_cmp_gt_u32 s87, 27
	s_nop 0
	v_writelane_b32 v245, s1, 53
	s_cselect_b64 s[0:1], -1, 0
	v_writelane_b32 v245, s0, 54
	s_cmp_gt_u32 s87, 28
	s_nop 0
	v_writelane_b32 v245, s1, 55
	s_cselect_b64 s[0:1], -1, 0
	v_writelane_b32 v245, s0, 56
	s_cmp_gt_u32 s87, 29
	s_nop 0
	v_writelane_b32 v245, s1, 57
	s_cselect_b64 s[0:1], -1, 0
	v_writelane_b32 v245, s0, 58
	s_nop 1
	v_writelane_b32 v245, s1, 59
	v_sub_co_u32_e64 v214, s[0:1], s2, 32
	s_xor_b64 s[0:1], s[0:1], -1
	s_nop 0
	v_writelane_b32 v245, s0, 60
	s_nop 1
	v_writelane_b32 v245, s1, 61
	s_sub_i32 s0, s94, 32
	v_writelane_b32 v245, s0, 62
	s_lshl_b32 s0, s3, 6
	s_addk_i32 s0, 0x2000
	v_writelane_b32 v245, s0, 63
	s_lshl_b32 s0, s3, 3
	s_cmpk_lt_i32 s2, 0x198
	v_writelane_b32 v244, s0, 0
	s_mul_hi_i32 s0, s2, 0x78787879
	s_cselect_b64 s[10:11], -1, 0
	v_writelane_b32 v244, s10, 1
	s_lshr_b32 s1, s0, 31
	s_ashr_i32 s0, s0, 6
	v_writelane_b32 v244, s11, 2
	s_add_i32 s10, s0, s1
	s_mul_i32 s0, s10, 0x88
	s_sub_i32 s0, s2, s0
	s_bfe_u32 s1, s0, 0x3001c
	s_add_i32 s1, s0, s1
	s_and_b32 s3, s1, 0xfff8
	s_sub_i32 s9, s0, s3
	s_sext_i32_i16 s0, s1
	s_ashr_i32 s11, s10, 31
	s_ashr_i32 s14, s0, 3
	s_lshl_b64 s[0:1], s[10:11], 11
	v_writelane_b32 v244, s0, 3
	s_nop 1
	v_writelane_b32 v244, s1, 4
	s_mov_b32 s0, s10
	v_writelane_b32 v244, s0, 5
	s_nop 1
	v_writelane_b32 v244, s1, 6
	s_lshl_b64 s[0:1], s[10:11], 21
	v_writelane_b32 v244, s0, 7
	s_cmpk_lt_i32 s2, 0x88
	s_nop 0
	v_writelane_b32 v244, s1, 8
	s_cselect_b64 s[0:1], -1, 0
	v_writelane_b32 v244, s0, 9
	s_cmpk_gt_u32 s2, 0x87
	s_nop 0
	v_writelane_b32 v244, s1, 10
	s_cselect_b64 s[0:1], -1, 0
	v_writelane_b32 v244, s0, 11
	s_nop 1
	v_writelane_b32 v244, s1, 12
	s_add_i32 s0, s84, 0xfffffbc0
	v_writelane_b32 v244, s0, 13
	s_add_i32 s0, s88, 0xfffffbc0
	s_cmpk_lt_i32 s2, 0x200
	v_writelane_b32 v244, s0, 14
	s_cselect_b64 s[0:1], -1, 0
	v_writelane_b32 v244, s0, 15
	s_ashr_i32 s3, s2, 31
	s_and_b32 s12, s2, 15
	v_writelane_b32 v244, s1, 16
	s_lshr_b32 s0, s3, 23
	s_add_i32 s0, s2, s0
	s_and_b32 s0, s0, 0xfe00
	s_sub_i32 s0, s2, s0
	s_sext_i32_i16 s1, s0
	s_bfe_u32 s1, s1, 0x3001c
	s_add_i32 s1, s0, s1
	s_and_b32 s4, s1, 0xfff8
	s_sub_i32 s15, s0, s4
	s_sext_i32_i16 s0, s1
	s_ashr_i32 s16, s0, 3
	v_readfirstlane_b32 s0, v0
	s_ashr_i32 s4, s0, 4
	s_add_i32 s10, s4, 32
	s_lshl_b32 s0, s4, 5
	s_ashr_i32 s11, s10, 31
	s_lshl_b32 s13, s12, 19
	s_ashr_i32 s1, s0, 31
	s_lshl_b32 s17, s15, 6
	v_writelane_b32 v244, s13, 17
	s_lshl_b64 s[18:19], s[10:11], 19
	v_writelane_b32 v244, s18, 18
	s_cmp_gt_i32 s4, -1
	s_nop 0
	v_writelane_b32 v244, s19, 19
	s_cselect_b64 s[18:19], -1, 0
	v_writelane_b32 v244, s18, 20
	s_ashr_i32 s11, s10, 3
	s_lshl_b32 s13, s10, 8
	v_writelane_b32 v244, s19, 21
	v_writelane_b32 v244, s11, 22
	s_lshl_b32 s10, s12, 8
	v_writelane_b32 v244, s10, 23
	s_and_b32 s56, s2, 7
	s_lshr_b32 s57, s2, 3
	s_and_b32 s58, s56, 1
	s_lshl_b32 s58, s58, 3
	s_add_i32 s58, s58, s57
	s_lshl_b32 s58, s58, 2
	s_lshr_b32 s59, s56, 1
	s_add_i32 s58, s58, s59
	s_sub_i32 s57, s57, 8
	s_mul_i32 s59, s56, 10
	s_lshr_b32 s60, s57, 1
	s_add_i32 s59, s59, s60
	s_lshl_b32 s59, s59, 1
	s_and_b32 s60, s57, 1
	s_add_i32 s59, s59, s60
	s_add_i32 s59, s59, 64
	s_cmpk_lt_u32 s2, 0xe0
	s_cselect_b32 s54, s59, s2
	s_cmpk_lt_u32 s2, 64
	s_cselect_b32 s54, s58, s54
	s_mov_b32 s55, 0
	s_lshl_b32 s10, s54, 4
	s_add_i32 s11, s10, 0x1200
	s_lshl_b32 s10, s54, 5
	s_add_i32 s18, s10, 0x400
	s_or_b32 s10, s13, 0x80
	v_writelane_b32 v244, s10, 24
	s_or_b32 s10, s13, 0x90
	v_writelane_b32 v244, s10, 25
	s_or_b32 s10, s13, 0xa0
	v_writelane_b32 v244, s10, 26
	v_writelane_b32 v244, s13, 27
	s_or_b32 s10, s13, 0xb0
	v_writelane_b32 v244, s10, 28
	s_add_i32 s10, s54, 1
	s_cmpk_lt_u32 s10, 0xe0
	s_cselect_b32 s12, 32, 16
	s_cmp_gt_i32 s54, 62
	s_cselect_b32 s19, s12, 48
	s_add_i32 s12, s54, 2
	s_cmpk_lt_u32 s12, 0xe0
	s_cselect_b32 s12, 32, 16
	s_cmp_gt_i32 s54, 61
	s_cselect_b32 s12, s12, 48
	s_add_i32 s20, s19, s12
	s_cmpk_gt_u32 s2, 0xdf
	s_cselect_b64 s[12:13], -1, 0
	v_writelane_b32 v244, s12, 29
	s_nop 1
	v_writelane_b32 v244, s13, 30
	s_and_b64 s[12:13], s[12:13], exec
	s_cselect_b32 s21, 16, 32
	s_cselect_b32 s22, s11, s18
	s_and_b64 s[12:13], vcc, exec
	s_cselect_b32 s11, s18, s11
	s_cmp_lt_i32 s54, 64
	s_mul_i32 s12, s54, 48
	s_cselect_b32 s13, s12, s22
	s_cselect_b32 s18, s12, s11
	s_cselect_b32 s21, 48, s21
	s_and_b32 s12, s13, 62
	s_ashr_i32 s11, s13, 6
	s_sub_i32 s12, 64, s12
	s_cmp_lt_u32 s12, s21
	v_mov_b32_e32 v0, s12
	s_cselect_b64 s[12:13], -1, 0
	v_sub_u32_e64 v0, s21, v0 clamp
	v_writelane_b32 v244, s12, 31
	s_add_i32 s11, s11, 1
	v_writelane_b32 v244, s13, 32
	s_lshr_b32 s92, s11, 2
	s_and_b32 s28, s11, 3
	s_sub_i32 s60, s11, 48
	s_lshr_b32 s62, s60, 2
	s_add_i32 s62, s62, 12
	s_and_b32 s63, s60, 3
	s_cmpk_lt_u32 s11, 0x80
	s_cselect_b32 s92, s62, s92
	s_cselect_b32 s28, s63, s28
	s_mul_i32 s61, s11, 43
	s_lshr_b32 s61, s61, 7
	s_mul_i32 s62, s61, 3
	s_sub_i32 s62, s11, s62
	s_lshl_b32 s62, s62, 2
	s_lshr_b32 s63, s61, 2
	s_add_i32 s62, s62, s63
	s_and_b32 s63, s61, 3
	s_cmpk_lt_u32 s11, 48
	s_cselect_b32 s92, s62, s92
	s_cselect_b32 s28, s63, s28
	v_readfirstlane_b32 s11, v0
	s_nop 1
	v_writelane_b32 v244, s11, 33
	s_sub_i32 s11, 64, s11
	s_cmp_gt_u32 s11, s19
	s_cselect_b32 s22, 2, 1
	s_cmp_gt_u32 s11, s20
	s_cselect_b64 s[12:13], -1, 0
	s_cmp_lg_u64 s[12:13], 0
	s_addc_u32 s11, s22, 0
	v_writelane_b32 v244, s11, 34
	s_ashr_i32 s11, s10, 31
	s_lshl_b64 s[10:11], s[10:11], 17
	v_writelane_b32 v244, s10, 35
	s_lshl_b64 s[12:13], s[54:55], 17
	s_nop 0
	v_writelane_b32 v244, s11, 36
	s_sext_i32_i16 s10, s8
	s_cmp_lt_i32 s10, 0
	s_cselect_b32 s10, s93, 0x66
	s_mul_i32 s8, s10, s8
	s_add_i32 s8, s8, s6
	s_sext_i32_i16 s6, s8
	s_mulk_i32 s6, 0x2aab
	s_lshr_b32 s10, s6, 31
	s_ashr_i32 s6, s6, 21
	s_add_i32 s6, s6, s10
	s_mul_i32 s10, s6, 0xc0
	s_sext_i32_i16 s6, s6
	s_lshl_b32 s11, s6, 3
	v_writelane_b32 v244, s12, 37
	s_sub_i32 s6, 34, s11
	s_sub_i32 s10, s8, s10
	v_writelane_b32 v244, s13, 38
	s_min_u32 s12, s6, 8
	s_sext_i32_i16 s6, s7
	s_cmp_lt_i32 s6, 0
	s_cselect_b32 s6, 52, 51
	s_mul_i32 s6, s6, s7
	s_add_i32 s6, s6, s5
	s_sext_i32_i16 s5, s6
	s_mulk_i32 s5, 0x2aab
	s_lshr_b32 s7, s5, 31
	s_ashr_i32 s5, s5, 20
	s_add_i32 s5, s5, s7
	s_mul_i32 s7, s5, 0x60
	s_sext_i32_i16 s5, s5
	s_lshl_b32 s5, s5, 3
	s_sub_i32 s13, s6, s7
	s_sub_i32 s6, 34, s5
	s_min_u32 s22, s6, 8
	s_sext_i32_i16 s6, s9
	s_cmp_lt_i32 s6, 0
	s_cselect_b32 s6, 18, 17
	s_mul_i32 s6, s6, s9
	s_add_i32 s6, s6, s14
	s_sext_i32_i16 s7, s6
	s_bfe_u32 s7, s7, 0x5001a
	s_add_i32 s7, s6, s7
	s_and_b32 s8, s7, 0xffe0
	s_sub_i32 s14, s6, s8
	s_sext_i32_i16 s6, s7
	s_ashr_i32 s6, s6, 5
	s_lshl_b32 s23, s6, 3
	s_sub_i32 s6, 34, s23
	s_min_u32 s24, s6, 8
	s_sext_i32_i16 s6, s15
	s_cmp_lt_i32 s6, 0
	s_mulk_i32 s15, 0x41
	s_cselect_b32 s6, s15, s17
	s_add_i32 s6, s6, s16
	s_sext_i32_i16 s7, s6
	s_bfe_u32 s7, s7, 0x70018
	s_add_i32 s7, s6, s7
	s_and_b32 s8, s7, 0xff80
	s_sub_i32 s6, s6, s8
	s_bfe_i32 s8, s6, 0x80000
	s_bfe_u32 s8, s8, 0x3000c
	s_add_i32 s8, s6, s8
	s_and_b32 s9, s8, 0xf8
	s_sext_i32_i16 s7, s7
	s_sub_i32 s6, s6, s9
	s_and_b32 s15, s18, 62
	s_ashr_i32 s7, s7, 7
	s_bfe_i32 s8, s8, 0x80000
	s_sub_i32 s9, 64, s15
	s_lshl_b32 s7, s7, 3
	s_sext_i32_i16 s8, s8
	s_sext_i32_i8 s6, s6
	s_min_u32 s9, s9, s21
	s_add_i32 s30, s7, s6
	s_ashr_i32 s6, s8, 3
	v_writelane_b32 v244, s6, 39
	s_lshr_b32 s6, s8, 3
	s_lshr_b32 s56, s18, 6
	s_lshr_b32 s18, s56, 2
	s_and_b32 s17, s56, 3
	s_sub_i32 s60, s56, 48
	s_lshr_b32 s62, s60, 2
	s_add_i32 s62, s62, 12
	s_and_b32 s63, s60, 3
	s_cmpk_lt_u32 s56, 0x80
	s_cselect_b32 s18, s62, s18
	s_cselect_b32 s17, s63, s17
	s_mul_i32 s61, s56, 43
	s_lshr_b32 s61, s61, 7
	s_mul_i32 s62, s61, 3
	s_sub_i32 s62, s56, s62
	s_lshl_b32 s62, s62, 2
	s_lshr_b32 s63, s61, 2
	s_add_i32 s62, s62, s63
	s_and_b32 s63, s61, 3
	s_cmpk_lt_u32 s56, 48
	s_cselect_b32 s18, s62, s18
	s_cselect_b32 s17, s63, s17
	s_sub_i32 s7, 64, s9
	s_cmp_gt_u32 s7, s19
	s_cselect_b32 s16, 2, 1
	s_cmp_gt_u32 s7, s20
	v_writelane_b32 v244, s9, 40
	s_cselect_b64 s[8:9], -1, 0
	s_cmp_lg_u64 s[8:9], 0
	s_addc_u32 s8, s16, 0
	s_bfe_i64 s[6:7], s[6:7], 0x100000
	s_lshl_b64 s[6:7], s[6:7], 19
	v_writelane_b32 v244, s6, 41
	s_ashr_i32 s19, s18, 31
	s_ashr_i32 s31, s30, 31
	v_writelane_b32 v244, s7, 42
	s_lshl_b32 s6, s15, 7
	v_writelane_b32 v244, s6, 43
	v_writelane_b32 v244, s17, 44
	s_lshl_b32 s6, s17, 21
	v_writelane_b32 v244, s6, 45
	s_mov_b32 s6, s18
	v_writelane_b32 v244, s6, 46
	v_cvt_f32_ubyte0_e32 v1, s12
	v_rcp_iflag_f32_e32 v2, v1
	v_writelane_b32 v244, s7, 47
	s_lshl_b64 s[6:7], s[18:19], 21
	v_writelane_b32 v244, s6, 48
	s_nop 1
	v_writelane_b32 v244, s7, 49
	s_mov_b32 s6, s30
	v_writelane_b32 v244, s6, 50
	s_nop 1
	v_writelane_b32 v244, s7, 51
	s_lshl_b64 s[6:7], s[30:31], 19
	v_writelane_b32 v244, s6, 52
	s_cmp_eq_u32 s15, 0
	s_nop 0
	v_writelane_b32 v244, s7, 53
	s_cselect_b32 s6, s8, 0
	v_writelane_b32 v244, s6, 54
	s_sext_i32_i16 s6, s10
	v_cvt_f32_i32_e32 v0, s6
	s_cselect_b32 s7, 2, 1
	s_ashr_i32 s6, s6, 30
	v_writelane_b32 v244, s7, 55
	v_mul_f32_e32 v2, v0, v2
	v_trunc_f32_e32 v2, v2
	v_fma_f32 v0, -v2, v1, v0
	s_or_b32 s8, s6, 1
	v_cmp_ge_f32_e64 s[6:7], |v0|, v1
	v_cvt_i32_f32_e32 v0, v2
	s_and_b64 s[6:7], s[6:7], exec
	s_cselect_b32 s6, s8, 0
	v_cvt_f32_ubyte0_e32 v1, s22
	v_readfirstlane_b32 s7, v0
	s_add_i32 s15, s7, s6
	s_mul_i32 s6, s15, s12
	s_sub_i32 s6, s10, s6
	s_sext_i32_i16 s6, s6
	s_add_i32 s6, s11, s6
	v_writelane_b32 v244, s6, 56
	s_sext_i32_i16 s6, s13
	v_cvt_f32_i32_e32 v0, s6
	v_rcp_iflag_f32_e32 v2, v1
	s_ashr_i32 s6, s6, 30
	s_or_b32 s8, s6, 1
	v_mul_f32_e32 v2, v0, v2
	v_trunc_f32_e32 v2, v2
	v_fma_f32 v0, -v2, v1, v0
	v_cmp_ge_f32_e64 s[6:7], |v0|, v1
	v_cvt_i32_f32_e32 v0, v2
	s_and_b64 s[6:7], s[6:7], exec
	s_cselect_b32 s6, s8, 0
	v_cvt_f32_ubyte0_e32 v1, s24
	v_readfirstlane_b32 s7, v0
	s_add_i32 s6, s7, s6
	s_mul_i32 s7, s6, s22
	s_sub_i32 s7, s13, s7
	s_sext_i32_i8 s7, s7
	s_add_i32 s10, s5, s7
	s_sext_i32_i16 s5, s14
	v_cvt_f32_i32_e32 v0, s5
	v_rcp_iflag_f32_e32 v2, v1
	s_bfe_i64 s[8:9], s[6:7], 0x80000
	s_lshl_b64 s[8:9], s[8:9], 18
	v_writelane_b32 v244, s8, 57
	s_ashr_i32 s11, s10, 31
	v_mul_f32_e32 v2, v0, v2
	v_writelane_b32 v244, s9, 58
	s_mov_b32 s8, s10
	v_writelane_b32 v244, s8, 59
	v_trunc_f32_e32 v2, v2
	v_fma_f32 v0, -v2, v1, v0
	v_writelane_b32 v244, s9, 60
	s_lshl_b64 s[8:9], s[10:11], 18
	v_writelane_b32 v244, s8, 61
	s_ashr_i32 s5, s5, 30
	s_or_b32 s5, s5, 1
	v_writelane_b32 v244, s9, 62
	v_cmp_ge_f32_e64 s[8:9], |v0|, v1
	v_cvt_i32_f32_e32 v0, v2
	s_and_b64 s[8:9], s[8:9], exec
	v_writelane_b32 v244, s26, 63
	s_sext_i32_i8 s6, s6
	s_cselect_b32 s5, s5, 0
	v_writelane_b32 v243, s27, 0
	v_writelane_b32 v243, s6, 1
	v_readfirstlane_b32 s6, v0
	s_add_i32 s6, s6, s5
	s_mul_i32 s5, s6, s24
	s_sub_i32 s5, s14, s5
	s_sext_i32_i8 s5, s5
	s_add_i32 s5, s23, s5
	s_mul_i32 s7, s95, s94
	v_writelane_b32 v243, s5, 2
	s_sext_i32_i16 s5, s15
	s_mul_i32 s95, s7, s33
	v_writelane_b32 v243, s5, 3
	s_sext_i32_i8 s5, s6
	s_bfe_i64 s[6:7], s[6:7], 0x80000
	v_writelane_b32 v243, s5, 4
	s_lshl_b64 s[6:7], s[6:7], 19
	v_writelane_b32 v243, s6, 5
	s_ashr_i32 s5, s4, 31
	s_lshl_b64 s[4:5], s[4:5], 19
	v_writelane_b32 v243, s7, 6
	v_writelane_b32 v243, s4, 7
	s_lshl_b64 s[0:1], s[0:1], 2
	s_ashr_i32 s85, s84, 31
	v_writelane_b32 v243, s5, 8
	v_writelane_b32 v243, s0, 9
	s_lshl_b32 s4, s94, 5
	v_mbcnt_lo_u32_b32 v0, -1, 0
	v_writelane_b32 v243, s1, 10
	v_writelane_b32 v243, s84, 11
	s_add_i32 s1, s84, 0xfffff800
	s_movk_i32 s0, 0x110
	v_writelane_b32 v243, s85, 12
	v_writelane_b32 v243, s1, 13
	s_lshl_b32 s1, s2, 5
	v_writelane_b32 v243, s1, 14
	s_addk_i32 s1, 0xdc00
	v_writelane_b32 v243, s1, 15
	v_writelane_b32 v243, s4, 16
	s_add_i32 s1, s4, 0xfffffc00
	v_writelane_b32 v243, s1, 17
	s_lshl_b32 s1, s94, 10
	v_writelane_b32 v243, s1, 18
	s_lshl_b32 s1, s2, 12
	v_writelane_b32 v243, s1, 19
	s_lshl_b32 s1, s94, 14
	v_writelane_b32 v243, s1, 20
	s_add_i32 s1, 0, 0x20000
	v_writelane_b32 v243, s1, 21
	s_add_i32 s1, 0, 0x20004
	v_writelane_b32 v243, s1, 22
	v_cmp_gt_i32_e64 s[0:1], s0, v214
	v_cndmask_b32_e64 v215, 0, 1, s[26:27]
	v_mbcnt_hi_u32_b32 v221, -1, v0
	v_writelane_b32 v243, s0, 23
	s_movk_i32 s33, 0x2000
	s_mov_b32 s84, s28
	v_writelane_b32 v243, s1, 24
	v_cmp_gt_u32_e64 s[0:1], 64, v195
	s_mov_b64 s[4:5], 0x80
	s_nop 0
	v_writelane_b32 v243, s0, 25
	s_nop 1
	v_writelane_b32 v243, s1, 26
	s_lshl_b64 s[0:1], s[54:55], 2
	v_writelane_b32 v243, s0, 27
	s_nop 1
	v_writelane_b32 v243, s1, 28
	v_writelane_b32 v243, s36, 29
	s_nop 1
	v_writelane_b32 v243, s37, 30
	v_writelane_b32 v243, s38, 31
	s_nop 1
	v_writelane_b32 v243, s39, 32
	v_writelane_b32 v243, s40, 33
	s_nop 1
	v_writelane_b32 v243, s41, 34
	v_writelane_b32 v243, s42, 35
	s_nop 1
	v_writelane_b32 v243, s43, 36
	v_writelane_b32 v243, s44, 37
	s_nop 1
	v_writelane_b32 v243, s45, 38
	v_writelane_b32 v243, s46, 39
	s_nop 1
	v_writelane_b32 v243, s47, 40
	v_writelane_b32 v243, s48, 41
	s_nop 1
	v_writelane_b32 v243, s49, 42
	v_writelane_b32 v243, s94, 43
	s_nop 1
	v_writelane_b32 v243, s95, 44
	v_writelane_b32 v243, s82, 45
	s_nop 1
	v_writelane_b32 v243, s83, 46
	v_writelane_b32 v243, s86, 47
	v_writelane_b32 v243, s80, 48
	v_writelane_b32 v243, s81, 49
	v_writelane_b32 v243, s87, 50
	v_writelane_b32 v243, s89, 51
	v_writelane_b32 v243, s95, 52
	s_branch .LBB0_414
